# grid barrier: non-leader workgroups poll the cross-XCD generation word directly instead of waiting for their XCD leader to relay it
# baseline (speedup 1.0000x reference)
; __device__ __forceinline__ unsigned xb_ld(unsigned* p)              { return __hip_atomic_load(p, __ATOMIC_RELAXED, __HIP_MEMORY_SCOPE_AGENT); }
; __device__ __forceinline__ unsigned xb_add(unsigned* p, unsigned v) { return __hip_atomic_fetch_add(p, v, __ATOMIC_RELAXED, __HIP_MEMORY_SCOPE_AGENT); }
; #define XB_SPIN(cond, bar) do { unsigned _sp = 0; while (cond) { __builtin_amdgcn_s_sleep(1); \
;     if ((++_sp & 255u) == 0u) { if (xb_ld(&(bar)[XB_TMO])) break; if (_sp > XB_SPIN_CAP) { atomicAdd(&(bar)[XB_TMO], 1u); break; } } } } while (0)
; __device__ __forceinline__ void xcd_barrier(const XcdBarrier& b) {
;     ...
;         const unsigned old = xb_add(&bar[XB_XSUB(b.x)], 1u);
;         const unsigned gen = old / nloc;
;         if (old + 1u == (gen + 1u) * nloc) {
;             __builtin_amdgcn_fence(__ATOMIC_RELEASE, "agent");
;             asm volatile("s_waitcnt vmcnt(0)" ::: "memory");
;             const unsigned og = xb_add(&bar[XB_TOP], 1u);
;             const unsigned tg = og / nx;
;             if (og + 1u == (tg + 1u) * nx) xb_add(&bar[XB_TOPGEN], 1u);
;             else XB_SPIN(xb_ld(&bar[XB_TOPGEN]) == tg, bar);
;             __builtin_amdgcn_fence(__ATOMIC_ACQUIRE, "agent");
;             xb_add(&bar[XB_XGEN(b.x)], 1u);
;             asm volatile("s_waitcnt vmcnt(0)" ::: "memory");
;         } else {
;             XB_SPIN(xb_ld(&bar[XB_XGEN(b.x)]) == gen, bar);
.LBB0_29:
	s_or_b64 exec, exec, s[6:7]
	v_cvt_f32_u32_e32 v4, v2
	s_waitcnt vmcnt(0)
	v_readfirstlane_b32 s6, v3
	v_sub_u32_e32 v3, 0, v2
	v_rcp_iflag_f32_e32 v4, v4
	v_add_u32_e32 v5, s6, v1
	v_mul_f32_e32 v4, 0x4f7ffffe, v4
	v_cvt_u32_f32_e32 v4, v4
	v_mul_lo_u32 v1, v3, v4
	v_mul_hi_u32 v1, v4, v1
	v_add_u32_e32 v1, v4, v1
	v_mul_hi_u32 v1, v5, v1
	v_mul_lo_u32 v3, v1, v2
	v_sub_u32_e32 v3, v5, v3
	v_add_u32_e32 v4, 1, v1
	v_cmp_ge_u32_e32 vcc, v3, v2
	s_nop 1
	v_cndmask_b32_e32 v1, v1, v4, vcc
	v_sub_u32_e32 v4, v3, v2
	v_cndmask_b32_e32 v3, v3, v4, vcc
	v_add_u32_e32 v4, 1, v1
	v_cmp_ge_u32_e32 vcc, v3, v2
	v_add_u32_e32 v3, 1, v5
	s_nop 0
	v_cndmask_b32_e32 v1, v1, v4, vcc
	v_mul_lo_u32 v4, v2, v1
	v_add_u32_e32 v2, v4, v2
	v_cmp_ne_u32_e32 vcc, v3, v2
	s_and_saveexec_b64 s[6:7], vcc
	s_xor_b64 s[6:7], exec, s[6:7]
	s_cbranch_execz .LBB0_43
	v_readlane_b32 s8, v254, 5
	v_readlane_b32 s9, v254, 6
	s_waitcnt lgkmcnt(0)
	s_nop 3
	global_load_dword v0, v177, s[8:9] sc1
	s_waitcnt vmcnt(0)
	v_cmp_eq_u32_e32 vcc, v0, v1
	s_and_saveexec_b64 s[8:9], vcc
	s_cbranch_execz .LBB0_42
	s_mov_b32 s20, 1
	s_mov_b64 s[10:11], 0
	s_branch .LBB0_33

; __device__ __forceinline__ unsigned xb_ld(unsigned* p)              { return __hip_atomic_load(p, __ATOMIC_RELAXED, __HIP_MEMORY_SCOPE_AGENT); }
; #define XB_SPIN(cond, bar) do { unsigned _sp = 0; while (cond) { __builtin_amdgcn_s_sleep(1); \
;     if ((++_sp & 255u) == 0u) { if (xb_ld(&(bar)[XB_TMO])) break; if (_sp > XB_SPIN_CAP) { atomicAdd(&(bar)[XB_TMO], 1u); break; } } } } while (0)
; __device__ __forceinline__ void xcd_barrier(const XcdBarrier& b) {
;     ...
;             XB_SPIN(xb_ld(&bar[XB_XGEN(b.x)]) == gen, bar);
;             __builtin_amdgcn_fence(__ATOMIC_ACQUIRE, "agent");
;             asm volatile("s_waitcnt vmcnt(0)" ::: "memory");
.LBB0_37:
	v_readlane_b32 s14, v254, 5
	v_readlane_b32 s15, v254, 6
	s_add_i32 s20, s20, 1
	s_mov_b64 s[16:17], -1
	s_nop 2
	global_load_dword v0, v177, s[14:15] sc1
	s_waitcnt vmcnt(0)
	v_cmp_ne_u32_e32 vcc, v0, v1
	s_orn2_b64 s[14:15], vcc, exec
	s_branch .LBB0_32
